# v075 + gate/up SwiGLU epilogue batched with packed f32 mul/add (same per-element op order, bit-identical outputs)
# baseline (speedup 1.0000x reference)
; __device__ __forceinline__ unsigned cvt_pk_bf16(float lo, float hi) { unsigned r; asm volatile("v_cvt_pk_bf16_f32 %0, %1, %2" : "=v"(r) : "v"(lo), "v"(hi)); return r; }
; __device__ __forceinline__ float silu_mul(float g, float u) { return g * __builtin_amdgcn_rcpf(1.0f + __builtin_amdgcn_exp2f(-1.4426950408889634f * g)) * u; }
;     __device__ __forceinline__ void operator()(const f32x4 (&acc)[2][2][4][2], const Unit& u, int wr, int wc, int fr, int fq) const {
;         const int row0 = u.pm * BM + wr * 64 + fr, col0 = u.pn * HALF + wc * 32 + 8 * fq;
; #pragma unroll
;         for (int ai = 0; ai < 2; ++ai)
; #pragma unroll
;             for (int m = 0; m < 4; ++m) { bf16_t* rowp = O + (size_t)(row0 + ai * HALF + m * 16) * ldc + col0;
;                 const f32x4 g0 = acc[ai][0][m][0], g1 = acc[ai][0][m][1], u0 = acc[ai][1][m][0], u1 = acc[ai][1][m][1];
;                 u32x4 w; w.x = cvt_pk_bf16(silu_mul(g0[0], u0[0]), silu_mul(g0[1], u0[1])); w.y = cvt_pk_bf16(silu_mul(g0[2], u0[2]), silu_mul(g0[3], u0[3]));
;                 w.z = cvt_pk_bf16(silu_mul(g1[0], u1[0]), silu_mul(g1[1], u1[1])); w.w = cvt_pk_bf16(silu_mul(g1[2], u1[2]), silu_mul(g1[3], u1[3]));
;                 *(u32x4*)rowp = w; }
.LBB0_1039:
	v_mov_b32_e32 v144, 0xbfb8aa3b
	v_mov_b32_e32 v145, 0xbfb8aa3b
	v_mov_b32_e32 v146, 1.0
	v_mov_b32_e32 v147, 1.0
	v_lshl_or_b32 v130, s4, 7, v137
	v_lshl_add_u32 v140, s56, 8, v136
	v_ashrrev_i32_e32 v131, 31, v130
	v_mov_b64_e32 v[128:129], s[18:19]
	v_mad_i64_i32 v[142:143], s[4:5], v140, s86, v[128:129]
	v_lshlrev_b64 v[130:131], 1, v[130:131]
	v_lshl_add_u64 v[142:143], v[142:143], 0, v[130:131]
	s_mov_b64 s[56:57], -1
	s_and_b64 vcc, exec, s[44:45]
	v_pk_mul_f32 v[150:151], v[124:125], v[144:145]
	v_pk_mul_f32 v[152:153], v[126:127], v[144:145]
	v_pk_mul_f32 v[154:155], v[116:117], v[144:145]
	v_pk_mul_f32 v[156:157], v[118:119], v[144:145]
	v_exp_f32_e32 v150, v150
	v_exp_f32_e32 v151, v151
	v_exp_f32_e32 v152, v152
	v_exp_f32_e32 v153, v153
	v_exp_f32_e32 v154, v154
	v_exp_f32_e32 v155, v155
	v_exp_f32_e32 v156, v156
	v_exp_f32_e32 v157, v157
	v_pk_add_f32 v[150:151], v[150:151], v[146:147]
	v_pk_add_f32 v[152:153], v[152:153], v[146:147]
	v_pk_add_f32 v[154:155], v[154:155], v[146:147]
	v_pk_add_f32 v[156:157], v[156:157], v[146:147]
	v_rcp_f32_e32 v150, v150
	v_rcp_f32_e32 v151, v151
	v_rcp_f32_e32 v152, v152
	v_rcp_f32_e32 v153, v153
	v_rcp_f32_e32 v154, v154
	v_rcp_f32_e32 v155, v155
	v_rcp_f32_e32 v156, v156
	v_rcp_f32_e32 v157, v157
	v_pk_mul_f32 v[150:151], v[124:125], v[150:151]
	v_pk_mul_f32 v[152:153], v[126:127], v[152:153]
	v_pk_mul_f32 v[154:155], v[116:117], v[154:155]
	v_pk_mul_f32 v[156:157], v[118:119], v[156:157]
	v_pk_mul_f32 v[150:151], v[150:151], v[120:121]
	v_pk_mul_f32 v[152:153], v[152:153], v[122:123]
	v_pk_mul_f32 v[154:155], v[154:155], v[112:113]
	v_pk_mul_f32 v[156:157], v[156:157], v[114:115]
	v_cvt_pk_bf16_f32 v120, v150, v151
	v_cvt_pk_bf16_f32 v121, v152, v153
	v_cvt_pk_bf16_f32 v122, v154, v155
	v_cvt_pk_bf16_f32 v123, v156, v157
	global_store_dwordx4 v[142:143], v[120:123], off
	v_or_b32_e32 v112, 16, v140
	v_mad_i64_i32 v[112:113], s[4:5], v112, s86, v[128:129]
	v_lshl_add_u64 v[112:113], v[112:113], 0, v[130:131]
	v_pk_mul_f32 v[160:161], v[108:109], v[144:145]
	v_pk_mul_f32 v[162:163], v[110:111], v[144:145]
	v_pk_mul_f32 v[164:165], v[100:101], v[144:145]
	v_pk_mul_f32 v[166:167], v[102:103], v[144:145]
	v_exp_f32_e32 v160, v160
	v_exp_f32_e32 v161, v161
	v_exp_f32_e32 v162, v162
	v_exp_f32_e32 v163, v163
	v_exp_f32_e32 v164, v164
	v_exp_f32_e32 v165, v165
	v_exp_f32_e32 v166, v166
	v_exp_f32_e32 v167, v167
	v_pk_add_f32 v[160:161], v[160:161], v[146:147]
	v_pk_add_f32 v[162:163], v[162:163], v[146:147]
	v_pk_add_f32 v[164:165], v[164:165], v[146:147]
	v_pk_add_f32 v[166:167], v[166:167], v[146:147]
	v_rcp_f32_e32 v160, v160
	v_rcp_f32_e32 v161, v161
	v_rcp_f32_e32 v162, v162
	v_rcp_f32_e32 v163, v163
	v_rcp_f32_e32 v164, v164
	v_rcp_f32_e32 v165, v165
	v_rcp_f32_e32 v166, v166
	v_rcp_f32_e32 v167, v167
	v_pk_mul_f32 v[160:161], v[108:109], v[160:161]
	v_pk_mul_f32 v[162:163], v[110:111], v[162:163]
	v_pk_mul_f32 v[164:165], v[100:101], v[164:165]
	v_pk_mul_f32 v[166:167], v[102:103], v[166:167]
	v_pk_mul_f32 v[160:161], v[160:161], v[104:105]
	v_pk_mul_f32 v[162:163], v[162:163], v[106:107]
	v_pk_mul_f32 v[164:165], v[164:165], v[96:97]
	v_pk_mul_f32 v[166:167], v[166:167], v[98:99]
	v_cvt_pk_bf16_f32 v104, v160, v161
	v_cvt_pk_bf16_f32 v105, v162, v163
	v_cvt_pk_bf16_f32 v106, v164, v165
	v_cvt_pk_bf16_f32 v107, v166, v167
	global_store_dwordx4 v[112:113], v[104:107], off
	v_or_b32_e32 v96, 32, v140
	v_mad_i64_i32 v[96:97], s[4:5], v96, s86, v[128:129]
	v_lshl_add_u64 v[96:97], v[96:97], 0, v[130:131]
	v_pk_mul_f32 v[150:151], v[92:93], v[144:145]
	v_pk_mul_f32 v[152:153], v[94:95], v[144:145]
	v_pk_mul_f32 v[154:155], v[84:85], v[144:145]
	v_pk_mul_f32 v[156:157], v[86:87], v[144:145]
	v_exp_f32_e32 v150, v150
	v_exp_f32_e32 v151, v151
	v_exp_f32_e32 v152, v152
	v_exp_f32_e32 v153, v153
	v_exp_f32_e32 v154, v154
	v_exp_f32_e32 v155, v155
	v_exp_f32_e32 v156, v156
	v_exp_f32_e32 v157, v157
	v_pk_add_f32 v[150:151], v[150:151], v[146:147]
	v_pk_add_f32 v[152:153], v[152:153], v[146:147]
	v_pk_add_f32 v[154:155], v[154:155], v[146:147]
	v_pk_add_f32 v[156:157], v[156:157], v[146:147]
	v_rcp_f32_e32 v150, v150
	v_rcp_f32_e32 v151, v151
	v_rcp_f32_e32 v152, v152
	v_rcp_f32_e32 v153, v153
	v_rcp_f32_e32 v154, v154
	v_rcp_f32_e32 v155, v155
	v_rcp_f32_e32 v156, v156
	v_rcp_f32_e32 v157, v157
	v_pk_mul_f32 v[150:151], v[92:93], v[150:151]
	v_pk_mul_f32 v[152:153], v[94:95], v[152:153]
	v_pk_mul_f32 v[154:155], v[84:85], v[154:155]
	v_pk_mul_f32 v[156:157], v[86:87], v[156:157]
	v_pk_mul_f32 v[150:151], v[150:151], v[88:89]
	v_pk_mul_f32 v[152:153], v[152:153], v[90:91]
	v_pk_mul_f32 v[154:155], v[154:155], v[80:81]
	v_pk_mul_f32 v[156:157], v[156:157], v[82:83]
	v_cvt_pk_bf16_f32 v88, v150, v151
	v_cvt_pk_bf16_f32 v89, v152, v153
	v_cvt_pk_bf16_f32 v90, v154, v155
	v_cvt_pk_bf16_f32 v91, v156, v157
	global_store_dwordx4 v[96:97], v[88:91], off
	v_or_b32_e32 v80, 48, v140
	v_mad_i64_i32 v[80:81], s[4:5], v80, s86, v[128:129]
	v_lshl_add_u64 v[80:81], v[80:81], 0, v[130:131]
	v_pk_mul_f32 v[160:161], v[76:77], v[144:145]
	v_pk_mul_f32 v[162:163], v[78:79], v[144:145]
	v_pk_mul_f32 v[164:165], v[68:69], v[144:145]
	v_pk_mul_f32 v[166:167], v[70:71], v[144:145]
	v_exp_f32_e32 v160, v160
	v_exp_f32_e32 v161, v161
	v_exp_f32_e32 v162, v162
	v_exp_f32_e32 v163, v163
	v_exp_f32_e32 v164, v164
	v_exp_f32_e32 v165, v165
	v_exp_f32_e32 v166, v166
	v_exp_f32_e32 v167, v167
	v_pk_add_f32 v[160:161], v[160:161], v[146:147]
	v_pk_add_f32 v[162:163], v[162:163], v[146:147]
	v_pk_add_f32 v[164:165], v[164:165], v[146:147]
	v_pk_add_f32 v[166:167], v[166:167], v[146:147]
	v_rcp_f32_e32 v160, v160
; __device__ __forceinline__ unsigned cvt_pk_bf16(float lo, float hi) { unsigned r; asm volatile("v_cvt_pk_bf16_f32 %0, %1, %2" : "=v"(r) : "v"(lo), "v"(hi)); return r; }
; __device__ __forceinline__ float silu_mul(float g, float u) { return g * __builtin_amdgcn_rcpf(1.0f + __builtin_amdgcn_exp2f(-1.4426950408889634f * g)) * u; }
;     __device__ __forceinline__ void operator()(const f32x4 (&acc)[2][2][4][2], const Unit& u, int wr, int wc, int fr, int fq) const {
;         const int row0 = u.pm * BM + wr * 64 + fr, col0 = u.pn * HALF + wc * 32 + 8 * fq;
; #pragma unroll
;         for (int ai = 0; ai < 2; ++ai)
; #pragma unroll
;             for (int m = 0; m < 4; ++m) { bf16_t* rowp = O + (size_t)(row0 + ai * HALF + m * 16) * ldc + col0;
;                 const f32x4 g0 = acc[ai][0][m][0], g1 = acc[ai][0][m][1], u0 = acc[ai][1][m][0], u1 = acc[ai][1][m][1];
;                 u32x4 w; w.x = cvt_pk_bf16(silu_mul(g0[0], u0[0]), silu_mul(g0[1], u0[1])); w.y = cvt_pk_bf16(silu_mul(g0[2], u0[2]), silu_mul(g0[3], u0[3]));
;                 w.z = cvt_pk_bf16(silu_mul(g1[0], u1[0]), silu_mul(g1[1], u1[1])); w.w = cvt_pk_bf16(silu_mul(g1[2], u1[2]), silu_mul(g1[3], u1[3]));
;                 *(u32x4*)rowp = w; }
	v_rcp_f32_e32 v161, v161
	v_rcp_f32_e32 v162, v162
	v_rcp_f32_e32 v163, v163
	v_rcp_f32_e32 v164, v164
	v_rcp_f32_e32 v165, v165
	v_rcp_f32_e32 v166, v166
	v_rcp_f32_e32 v167, v167
	v_pk_mul_f32 v[160:161], v[76:77], v[160:161]
	v_pk_mul_f32 v[162:163], v[78:79], v[162:163]
	v_pk_mul_f32 v[164:165], v[68:69], v[164:165]
	v_pk_mul_f32 v[166:167], v[70:71], v[166:167]
	v_pk_mul_f32 v[160:161], v[160:161], v[72:73]
	v_pk_mul_f32 v[162:163], v[162:163], v[74:75]
	v_pk_mul_f32 v[164:165], v[164:165], v[64:65]
	v_pk_mul_f32 v[166:167], v[166:167], v[66:67]
	v_cvt_pk_bf16_f32 v72, v160, v161
	v_cvt_pk_bf16_f32 v73, v162, v163
	v_cvt_pk_bf16_f32 v74, v164, v165
	v_cvt_pk_bf16_f32 v75, v166, v167
	global_store_dwordx4 v[80:81], v[72:75], off
	v_add_u32_e32 v64, 0x80, v140
	v_mad_i64_i32 v[64:65], s[4:5], v64, s86, v[128:129]
	v_lshl_add_u64 v[64:65], v[64:65], 0, v[130:131]
	v_pk_mul_f32 v[150:151], v[60:61], v[144:145]
	v_pk_mul_f32 v[152:153], v[62:63], v[144:145]
	v_pk_mul_f32 v[154:155], v[52:53], v[144:145]
	v_pk_mul_f32 v[156:157], v[54:55], v[144:145]
	v_exp_f32_e32 v150, v150
	v_exp_f32_e32 v151, v151
	v_exp_f32_e32 v152, v152
	v_exp_f32_e32 v153, v153
	v_exp_f32_e32 v154, v154
	v_exp_f32_e32 v155, v155
	v_exp_f32_e32 v156, v156
	v_exp_f32_e32 v157, v157
	v_pk_add_f32 v[150:151], v[150:151], v[146:147]
	v_pk_add_f32 v[152:153], v[152:153], v[146:147]
	v_pk_add_f32 v[154:155], v[154:155], v[146:147]
	v_pk_add_f32 v[156:157], v[156:157], v[146:147]
	v_rcp_f32_e32 v150, v150
	v_rcp_f32_e32 v151, v151
	v_rcp_f32_e32 v152, v152
	v_rcp_f32_e32 v153, v153
	v_rcp_f32_e32 v154, v154
	v_rcp_f32_e32 v155, v155
	v_rcp_f32_e32 v156, v156
	v_rcp_f32_e32 v157, v157
	v_pk_mul_f32 v[150:151], v[60:61], v[150:151]
	v_pk_mul_f32 v[152:153], v[62:63], v[152:153]
	v_pk_mul_f32 v[154:155], v[52:53], v[154:155]
	v_pk_mul_f32 v[156:157], v[54:55], v[156:157]
	v_pk_mul_f32 v[150:151], v[150:151], v[56:57]
	v_pk_mul_f32 v[152:153], v[152:153], v[58:59]
	v_pk_mul_f32 v[154:155], v[154:155], v[48:49]
	v_pk_mul_f32 v[156:157], v[156:157], v[50:51]
	v_cvt_pk_bf16_f32 v56, v150, v151
	v_cvt_pk_bf16_f32 v57, v152, v153
	v_cvt_pk_bf16_f32 v58, v154, v155
	v_cvt_pk_bf16_f32 v59, v156, v157
	global_store_dwordx4 v[64:65], v[56:59], off
	v_add_u32_e32 v48, 0x90, v140
	v_mad_i64_i32 v[48:49], s[4:5], v48, s86, v[128:129]
	v_lshl_add_u64 v[48:49], v[48:49], 0, v[130:131]
	v_pk_mul_f32 v[160:161], v[44:45], v[144:145]
	v_pk_mul_f32 v[162:163], v[46:47], v[144:145]
	v_pk_mul_f32 v[164:165], v[36:37], v[144:145]
	v_pk_mul_f32 v[166:167], v[38:39], v[144:145]
	v_exp_f32_e32 v160, v160
	v_exp_f32_e32 v161, v161
	v_exp_f32_e32 v162, v162
	v_exp_f32_e32 v163, v163
	v_exp_f32_e32 v164, v164
	v_exp_f32_e32 v165, v165
	v_exp_f32_e32 v166, v166
	v_exp_f32_e32 v167, v167
	v_pk_add_f32 v[160:161], v[160:161], v[146:147]
	v_pk_add_f32 v[162:163], v[162:163], v[146:147]
	v_pk_add_f32 v[164:165], v[164:165], v[146:147]
	v_pk_add_f32 v[166:167], v[166:167], v[146:147]
	v_rcp_f32_e32 v160, v160
	v_rcp_f32_e32 v161, v161
	v_rcp_f32_e32 v162, v162
	v_rcp_f32_e32 v163, v163
	v_rcp_f32_e32 v164, v164
	v_rcp_f32_e32 v165, v165
	v_rcp_f32_e32 v166, v166
	v_rcp_f32_e32 v167, v167
	v_pk_mul_f32 v[160:161], v[44:45], v[160:161]
	v_pk_mul_f32 v[162:163], v[46:47], v[162:163]
	v_pk_mul_f32 v[164:165], v[36:37], v[164:165]
	v_pk_mul_f32 v[166:167], v[38:39], v[166:167]
	v_pk_mul_f32 v[160:161], v[160:161], v[40:41]
	v_pk_mul_f32 v[162:163], v[162:163], v[42:43]
	v_pk_mul_f32 v[164:165], v[164:165], v[32:33]
	v_pk_mul_f32 v[166:167], v[166:167], v[34:35]
	v_cvt_pk_bf16_f32 v40, v160, v161
	v_cvt_pk_bf16_f32 v41, v162, v163
	v_cvt_pk_bf16_f32 v42, v164, v165
	v_cvt_pk_bf16_f32 v43, v166, v167
	global_store_dwordx4 v[48:49], v[40:43], off
	v_add_u32_e32 v32, 0xa0, v140
	v_mad_i64_i32 v[32:33], s[4:5], v32, s86, v[128:129]
	v_lshl_add_u64 v[32:33], v[32:33], 0, v[130:131]
	v_pk_mul_f32 v[150:151], v[28:29], v[144:145]
	v_pk_mul_f32 v[152:153], v[30:31], v[144:145]
	v_pk_mul_f32 v[154:155], v[20:21], v[144:145]
	v_pk_mul_f32 v[156:157], v[22:23], v[144:145]
	v_exp_f32_e32 v150, v150
	v_exp_f32_e32 v151, v151
	v_exp_f32_e32 v152, v152
	v_exp_f32_e32 v153, v153
	v_exp_f32_e32 v154, v154
	v_exp_f32_e32 v155, v155
	v_exp_f32_e32 v156, v156
	v_exp_f32_e32 v157, v157
	v_pk_add_f32 v[150:151], v[150:151], v[146:147]
	v_pk_add_f32 v[152:153], v[152:153], v[146:147]
	v_pk_add_f32 v[154:155], v[154:155], v[146:147]
	v_pk_add_f32 v[156:157], v[156:157], v[146:147]
	v_rcp_f32_e32 v150, v150
	v_rcp_f32_e32 v151, v151
	v_rcp_f32_e32 v152, v152
	v_rcp_f32_e32 v153, v153
	v_rcp_f32_e32 v154, v154
	v_rcp_f32_e32 v155, v155
	v_rcp_f32_e32 v156, v156
	v_rcp_f32_e32 v157, v157
	v_pk_mul_f32 v[150:151], v[28:29], v[150:151]
	v_pk_mul_f32 v[152:153], v[30:31], v[152:153]
	v_pk_mul_f32 v[154:155], v[20:21], v[154:155]
	v_pk_mul_f32 v[156:157], v[22:23], v[156:157]
	v_pk_mul_f32 v[150:151], v[150:151], v[24:25]
	v_pk_mul_f32 v[152:153], v[152:153], v[26:27]
	v_pk_mul_f32 v[154:155], v[154:155], v[16:17]
	v_pk_mul_f32 v[156:157], v[156:157], v[18:19]
	v_cvt_pk_bf16_f32 v24, v150, v151
	v_cvt_pk_bf16_f32 v25, v152, v153
	v_cvt_pk_bf16_f32 v26, v154, v155
	v_cvt_pk_bf16_f32 v27, v156, v157
	global_store_dwordx4 v[32:33], v[24:27], off
	v_add_u32_e32 v16, 0xb0, v140
	v_mad_i64_i32 v[16:17], s[4:5], v16, s86, v[128:129]
	v_lshl_add_u64 v[16:17], v[16:17], 0, v[130:131]
	v_pk_mul_f32 v[160:161], v[12:13], v[144:145]
	v_pk_mul_f32 v[162:163], v[14:15], v[144:145]
	v_pk_mul_f32 v[164:165], v[4:5], v[144:145]
	v_pk_mul_f32 v[166:167], v[6:7], v[144:145]
	v_exp_f32_e32 v160, v160
	v_exp_f32_e32 v161, v161
	v_exp_f32_e32 v162, v162
	v_exp_f32_e32 v163, v163
	v_exp_f32_e32 v164, v164
	v_exp_f32_e32 v165, v165
	v_exp_f32_e32 v166, v166
	v_exp_f32_e32 v167, v167
	v_pk_add_f32 v[160:161], v[160:161], v[146:147]
	v_pk_add_f32 v[162:163], v[162:163], v[146:147]
	v_pk_add_f32 v[164:165], v[164:165], v[146:147]
	v_pk_add_f32 v[166:167], v[166:167], v[146:147]
	v_rcp_f32_e32 v160, v160
	v_rcp_f32_e32 v161, v161
	v_rcp_f32_e32 v162, v162
	v_rcp_f32_e32 v163, v163
	v_rcp_f32_e32 v164, v164
	v_rcp_f32_e32 v165, v165
	v_rcp_f32_e32 v166, v166
	v_rcp_f32_e32 v167, v167
	v_pk_mul_f32 v[160:161], v[12:13], v[160:161]
	v_pk_mul_f32 v[162:163], v[14:15], v[162:163]
	v_pk_mul_f32 v[164:165], v[4:5], v[164:165]
	v_pk_mul_f32 v[166:167], v[6:7], v[166:167]
	v_pk_mul_f32 v[160:161], v[160:161], v[8:9]
	v_pk_mul_f32 v[162:163], v[162:163], v[10:11]
	v_pk_mul_f32 v[164:165], v[164:165], v[0:1]
	v_pk_mul_f32 v[166:167], v[166:167], v[2:3]
	v_cvt_pk_bf16_f32 v8, v160, v161
	v_cvt_pk_bf16_f32 v9, v162, v163
	v_cvt_pk_bf16_f32 v10, v164, v165
	v_cvt_pk_bf16_f32 v11, v166, v167
	global_store_dwordx4 v[16:17], v[8:11], off
	s_cbranch_vccnz .LBB0_1028
	s_andn2_b64 vcc, exec, s[16:17]
	s_cbranch_vccnz .LBB0_1027
	s_barrier
	s_branch .LBB0_1027
